# MLA loop: s_setprio 1 over the QK MFMA segment and over the PV MFMA tail, 0 over the softmax vector work
# baseline (speedup 1.0000x reference)
;     ...
;         if (!wdone && 64 * j <= qw0 + 31) {
;             const unsigned char* kb = lds + st * STG;
;             const unsigned char* vb = kb + KBYTES;
;             f32x16 s[2];
;             if (FOX) {
;                 const float* bl = (const float*)(vb + VBYTES);
; #pragma unroll
;                 for (int t2 = 0; t2 < 2; ++t2)
; #pragma unroll
;                     for (int g = 0; g < 4; ++g) {
;                         const f32x4 b4 = *(const f32x4*)(bl + t2 * 32 + 8 * g + 4 * h);
;                         s[t2][4 * g] = b4[0]; s[t2][4 * g + 1] = b4[1]; s[t2][4 * g + 2] = b4[2]; s[t2][4 * g + 3] = b4[3];
;                     }
;             } else {
; #pragma unroll
;                 for (int t2 = 0; t2 < 2; ++t2)
; #pragma unroll
;                     for (int r = 0; r < 16; ++r) s[t2][r] = 0.f;
;             }
;             bf16x8 kf[KS][2];
; #pragma unroll
;             for (int ks = 0; ks < KS; ++ks)
; #pragma unroll
;                 for (int t2 = 0; t2 < 2; ++t2) kf[ks][t2] = *(const bf16x8*)(kb + (t2 * 32 + ln) * KROW + ks * 32 + h * 16);
;             __builtin_amdgcn_sched_barrier(0);
; #pragma unroll
;             for (int ks = 0; ks < KS; ++ks)
; #pragma unroll
;                 for (int t2 = 0; t2 < 2; ++t2) s[t2] = __builtin_amdgcn_mfma_f32_32x32x16_bf16(kf[ks][t2], qf[ks], s[t2], 0, 0, 0);
;             __builtin_amdgcn_sched_barrier(0);
;             u32x2 vf[4][2][2];
; #pragma unroll
;             for (int kk = 0; kk < 4; ++kk)
; #pragma unroll
;                 for (int d = 0; d < 2; ++d) {
;                     const unsigned char* va = vb + (d * 32 + ln) * VROW + (16 * kk + 4 * h) * 2;
;                     vf[kk][d][0] = *(const u32x2*)va; vf[kk][d][1] = *(const u32x2*)(va + 16);
;                 }
;             __builtin_amdgcn_sched_barrier(0);
;             if (64 * j + 63 > qw0) {
;                 const int thr = myq - 64 * j - 4 * h;
; #pragma unroll
;                 for (int t2 = 0; t2 < 2; ++t2)
; #pragma unroll
;                     for (int r = 0; r < 16; ++r) { if (((r & 3) + 8 * (r >> 2) + 32 * t2) > thr) s[t2][r] = -INFINITY; }
;             }
.LBB0_754:
	s_add_i32 s8, s42, 64
	s_and_b32 s61, s60, 1
	v_cmp_le_i32_e32 vcc, s8, v218
	s_and_saveexec_b64 s[66:67], vcc
	s_cbranch_execz .LBB0_760
	s_mul_i32 s8, s61, 0x5700
	s_add_i32 s8, s8, 0
	v_add3_u32 v1, s8, v150, v200
	ds_read_b128 v[34:37], v1 offset:2048
	ds_read_b128 v[102:105], v1 offset:2080
	ds_read_b128 v[38:41], v1 offset:8704
	ds_read_b128 v[106:109], v1 offset:8736
	ds_read_b128 v[110:113], v1 offset:2112
	ds_read_b128 v[114:117], v1 offset:2144
	ds_read_b128 v[118:121], v1 offset:8768
	ds_read_b128 v[122:125], v1 offset:8800
	ds_read_b128 v[126:129], v1 offset:2176
	ds_read_b128 v[130:133], v1 offset:2208
	ds_read_b128 v[222:225], v1 offset:8832
	ds_read_b128 v[226:229], v1 offset:8864
	s_setprio 1
	s_waitcnt lgkmcnt(11)
	v_mfma_f32_32x32x16_bf16 v[50:65], v[34:37], v[66:69], v[230:245]
	s_waitcnt lgkmcnt(9)
	v_mfma_f32_32x32x16_bf16 v[34:49], v[38:41], v[66:69], v[230:245]
	v_mfma_f32_32x32x16_bf16 v[50:65], v[102:105], v[70:73], v[50:65]
	s_waitcnt lgkmcnt(8)
	v_mfma_f32_32x32x16_bf16 v[34:49], v[106:109], v[70:73], v[34:49]
	s_waitcnt lgkmcnt(7)
	v_mfma_f32_32x32x16_bf16 v[50:65], v[110:113], v[74:77], v[50:65]
	s_waitcnt lgkmcnt(5)
	v_mfma_f32_32x32x16_bf16 v[34:49], v[118:121], v[74:77], v[34:49]
	v_mfma_f32_32x32x16_bf16 v[50:65], v[114:117], v[78:81], v[50:65]
	s_waitcnt lgkmcnt(4)
	v_mfma_f32_32x32x16_bf16 v[34:49], v[122:125], v[78:81], v[34:49]
	s_waitcnt lgkmcnt(3)
	v_mfma_f32_32x32x16_bf16 v[50:65], v[126:129], v[82:85], v[50:65]
	s_waitcnt lgkmcnt(1)
	v_mfma_f32_32x32x16_bf16 v[34:49], v[222:225], v[82:85], v[34:49]
	v_mfma_f32_32x32x16_bf16 v[50:65], v[130:133], v[86:89], v[50:65]
	s_waitcnt lgkmcnt(0)
	v_mfma_f32_32x32x16_bf16 v[34:49], v[226:229], v[86:89], v[34:49]
	s_setprio 0
	v_add3_u32 v1, s8, v152, v181
	v_add_u32_e32 v102, 0x3800, v1
	v_add_u32_e32 v1, 0x4800, v1
	ds_read2_b64 v[130:133], v102 offset0:128 offset1:130
	ds_read2_b64 v[122:125], v102 offset0:132 offset1:134
	ds_read2_b64 v[126:129], v1 offset0:160 offset1:162
	ds_read2_b64 v[118:121], v1 offset0:164 offset1:166
	ds_read2_b64 v[114:117], v102 offset0:136 offset1:138
	ds_read2_b64 v[110:113], v1 offset0:168 offset1:170
	ds_read2_b64 v[106:109], v102 offset0:140 offset1:142
	ds_read2_b64 v[102:105], v1 offset0:172 offset1:174
	s_add_i32 s8, s42, 0x7f
	v_cmp_gt_i32_e32 vcc, s8, v159
	s_and_saveexec_b64 s[68:69], vcc
	s_cbranch_execz .LBB0_757
	v_cmp_gt_i32_e32 vcc, 0, v219
	v_cmp_gt_i32_e64 s[8:9], 1, v219
	s_and_b64 vcc, s[8:9], vcc
	v_cndmask_b32_e32 v50, v50, v217, vcc
	v_cmp_lt_i32_e32 vcc, 1, v219
	v_cmp_gt_i32_e64 s[38:39], 58, v219
	v_cmp_gt_i32_e64 s[40:41], 59, v219
	v_cndmask_b32_e32 v52, v217, v52, vcc
	v_cmp_lt_i32_e32 vcc, 2, v219
	v_cmp_gt_i32_e64 s[36:37], 57, v219
	s_and_b64 s[38:39], s[40:41], s[38:39]
	v_cndmask_b32_e32 v53, v217, v53, vcc
	v_cmp_lt_i32_e32 vcc, 7, v219
	v_cmp_gt_i32_e64 s[34:35], 56, v219
	s_and_b64 s[36:37], s[38:39], s[36:37]
	v_cndmask_b32_e32 v54, v217, v54, vcc
	v_cmp_lt_i32_e32 vcc, 8, v219
	v_cmp_gt_i32_e64 s[30:31], 51, v219
	s_and_b64 s[34:35], s[36:37], s[34:35]
	v_cndmask_b32_e32 v55, v217, v55, vcc
	v_cmp_lt_i32_e32 vcc, 9, v219
	v_cmp_gt_i32_e64 s[28:29], 50, v219
	s_and_b64 s[30:31], s[34:35], s[30:31]
	v_cndmask_b32_e32 v56, v217, v56, vcc
	v_cmp_lt_i32_e32 vcc, 10, v219
	v_cmp_gt_i32_e64 s[26:27], 49, v219
	s_and_b64 s[28:29], s[30:31], s[28:29]
	v_cndmask_b32_e32 v57, v217, v57, vcc
	v_cmp_lt_i32_e32 vcc, 15, v219
	v_cmp_gt_i32_e64 s[24:25], 48, v219
	s_and_b64 s[26:27], s[28:29], s[26:27]
	v_cndmask_b32_e32 v58, v217, v58, vcc
	v_cmp_lt_i32_e32 vcc, 16, v219
	v_cmp_gt_i32_e64 s[22:23], 43, v219
	s_and_b64 s[24:25], s[26:27], s[24:25]
	v_cndmask_b32_e32 v59, v217, v59, vcc
	v_cmp_lt_i32_e32 vcc, 17, v219
	v_cmp_gt_i32_e64 s[20:21], 42, v219
	s_and_b64 s[22:23], s[24:25], s[22:23]
	v_cndmask_b32_e32 v60, v217, v60, vcc
	v_cmp_lt_i32_e32 vcc, 18, v219
	v_cmp_gt_i32_e64 s[18:19], 41, v219
	s_and_b64 s[20:21], s[22:23], s[20:21]
	v_cndmask_b32_e32 v61, v217, v61, vcc
	v_cmp_lt_i32_e32 vcc, 23, v219
	v_cmp_gt_i32_e64 s[14:15], 40, v219
	s_and_b64 s[18:19], s[20:21], s[18:19]
	v_cndmask_b32_e32 v62, v217, v62, vcc
	v_cmp_lt_i32_e32 vcc, 24, v219
	v_cmp_gt_i32_e64 s[12:13], 35, v219
	s_and_b64 s[14:15], s[18:19], s[14:15]
	v_cndmask_b32_e32 v63, v217, v63, vcc
	v_cmp_lt_i32_e32 vcc, 25, v219
	v_cmp_gt_i32_e64 s[10:11], 34, v219
	s_and_b64 s[12:13], s[14:15], s[12:13]
	v_cndmask_b32_e64 v51, v51, v217, s[8:9]
	v_cndmask_b32_e32 v64, v217, v64, vcc
	v_cmp_lt_i32_e32 vcc, 26, v219
	v_cmp_gt_i32_e64 s[8:9], 33, v219
	s_and_b64 s[10:11], s[12:13], s[10:11]
	v_cndmask_b32_e32 v1, v217, v65, vcc
	v_cmp_gt_i32_e32 vcc, 32, v219
	s_and_b64 s[8:9], s[10:11], s[8:9]
	s_and_b64 vcc, s[8:9], vcc
	v_cndmask_b32_e64 v49, v49, v217, s[40:41]
	v_cndmask_b32_e64 v48, v48, v217, s[38:39]
	v_cndmask_b32_e64 v47, v47, v217, s[36:37]
	v_cndmask_b32_e64 v46, v46, v217, s[34:35]
	v_cndmask_b32_e64 v45, v45, v217, s[30:31]
	v_cndmask_b32_e64 v44, v44, v217, s[28:29]
	v_cndmask_b32_e64 v43, v43, v217, s[26:27]
	v_cndmask_b32_e64 v42, v42, v217, s[24:25]
	v_cndmask_b32_e64 v41, v41, v217, s[22:23]
	v_cndmask_b32_e64 v40, v40, v217, s[20:21]
	v_cndmask_b32_e64 v39, v39, v217, s[18:19]
	v_cndmask_b32_e64 v38, v38, v217, s[14:15]
	v_cndmask_b32_e64 v37, v37, v217, s[12:13]
	v_cndmask_b32_e64 v36, v36, v217, s[10:11]
	v_cndmask_b32_e64 v35, v35, v217, s[8:9]
	v_cndmask_b32_e32 v65, v65, v1, vcc
	v_cndmask_b32_e32 v34, v34, v217, vcc

; DI unsigned pk2(float lo, float hi) { f32x2 v = {lo, hi}; bf2_t b = __builtin_convertvector(v, bf2_t); return __builtin_bit_cast(unsigned, b); }
;     ...
;             float ps0 = 0.f, ps1 = 0.f, ps2 = 0.f, ps3 = 0.f;
; #pragma unroll
;             for (int t2 = 0; t2 < 2; ++t2)
; #pragma unroll
;                 for (int r = 0; r < 16; r += 4) {
;                     const float e0 = __builtin_amdgcn_exp2f(s[t2][r] - m), e1 = __builtin_amdgcn_exp2f(s[t2][r + 1] - m);
;                     const float e2 = __builtin_amdgcn_exp2f(s[t2][r + 2] - m), e3 = __builtin_amdgcn_exp2f(s[t2][r + 3] - m);
;                     s[t2][r] = e0; s[t2][r + 1] = e1; s[t2][r + 2] = e2; s[t2][r + 3] = e3;
;                     ps0 += e0; ps1 += e1; ps2 += e2; ps3 += e3;
;                 }
;             lsum += (ps0 + ps1) + (ps2 + ps3);
; #pragma unroll
;             for (int kk = 0; kk < 4; ++kk) {
;                 const int t2 = kk >> 1, s8 = (kk & 1) * 8;
;                 u32x4 pw;
;                 pw[0] = pk2(s[t2][s8 + 0], s[t2][s8 + 1]); pw[1] = pk2(s[t2][s8 + 2], s[t2][s8 + 3]);
;                 pw[2] = pk2(s[t2][s8 + 4], s[t2][s8 + 5]); pw[3] = pk2(s[t2][s8 + 6], s[t2][s8 + 7]);
;                 const bf16x8 pf = __builtin_bit_cast(bf16x8, pw);
; #pragma unroll
;                 for (int d = 0; d < 2; ++d) {
;                     const u32x4 vw = {vf[kk][d][0][0], vf[kk][d][0][1], vf[kk][d][1][0], vf[kk][d][1][1]};
;                     o[d] = __builtin_amdgcn_mfma_f32_32x32x16_bf16(__builtin_bit_cast(bf16x8, vw), pf, o[d], 0, 0, 0);
;                 }
;             }
.LBB0_759:
	v_exp_f32_e32 v50, v50
	v_exp_f32_e32 v222, v51
	v_add_f32_e32 v248, v248, v50
	v_exp_f32_e32 v51, v52
	v_add_f32_e32 v249, v249, v222
	v_exp_f32_e32 v223, v53
	v_add_f32_e32 v250, v250, v51
	v_exp_f32_e32 v52, v54
	v_add_f32_e32 v251, v251, v223
	v_exp_f32_e32 v54, v55
	v_add_f32_e32 v252, v252, v52
	v_exp_f32_e32 v53, v56
	v_add_f32_e32 v253, v253, v54
	v_exp_f32_e32 v55, v57
	v_add_f32_e32 v254, v254, v53
	v_exp_f32_e32 v56, v58
	v_add_f32_e32 v255, v255, v55
	v_exp_f32_e32 v58, v59
	v_add_f32_e32 v248, v248, v56
	v_exp_f32_e32 v57, v60
	v_add_f32_e32 v249, v249, v58
	v_exp_f32_e32 v59, v61
	v_add_f32_e32 v250, v250, v57
	v_exp_f32_e32 v60, v62
	v_add_f32_e32 v251, v251, v59
	v_exp_f32_e32 v62, v63
	v_add_f32_e32 v252, v252, v60
	v_exp_f32_e32 v61, v64
	v_add_f32_e32 v253, v253, v62
	v_exp_f32_e32 v63, v65
	v_add_f32_e32 v254, v254, v61
	v_exp_f32_e32 v64, v34
	v_add_f32_e32 v255, v255, v63
	v_exp_f32_e32 v224, v35
	v_add_f32_e32 v248, v248, v64
	v_exp_f32_e32 v65, v36
	v_add_f32_e32 v249, v249, v224
	v_exp_f32_e32 v225, v37
	v_add_f32_e32 v250, v250, v65
	v_cvt_pk_bf16_f32 v34, v50, v222
	v_add_f32_e32 v251, v251, v225
	v_cvt_pk_bf16_f32 v35, v51, v223
	v_cvt_pk_bf16_f32 v36, v52, v54
	v_cvt_pk_bf16_f32 v37, v53, v55
	s_setprio 1
	s_waitcnt lgkmcnt(7)
	s_nop 0
	v_mfma_f32_32x32x16_bf16 v[18:33], v[130:133], v[34:37], v[18:33]
	v_exp_f32_e32 v38, v38
	v_exp_f32_e32 v226, v39
	v_add_f32_e32 v252, v252, v38
	v_exp_f32_e32 v39, v40
	v_add_f32_e32 v253, v253, v226
	v_exp_f32_e32 v227, v41
	v_add_f32_e32 v254, v254, v39
	s_waitcnt lgkmcnt(5)
	v_add_f32_e32 v255, v255, v227
	v_mfma_f32_32x32x16_bf16 v[2:17], v[126:129], v[34:37], v[2:17]
	v_cvt_pk_bf16_f32 v34, v56, v58
	v_cvt_pk_bf16_f32 v35, v57, v59
	v_cvt_pk_bf16_f32 v36, v60, v62
	v_cvt_pk_bf16_f32 v37, v61, v63
	v_exp_f32_e32 v40, v42
	s_nop 0
	v_mfma_f32_32x32x16_bf16 v[18:33], v[122:125], v[34:37], v[18:33]
	v_add_f32_e32 v248, v248, v40
	v_exp_f32_e32 v42, v43
	v_exp_f32_e32 v41, v44
	v_add_f32_e32 v249, v249, v42
	v_exp_f32_e32 v43, v45
	v_add_f32_e32 v250, v250, v41
	v_exp_f32_e32 v44, v46
	v_add_f32_e32 v251, v251, v43
	s_waitcnt lgkmcnt(4)
	v_add_f32_e32 v252, v252, v44
	v_mfma_f32_32x32x16_bf16 v[2:17], v[118:121], v[34:37], v[2:17]
	v_cvt_pk_bf16_f32 v34, v64, v224
	v_cvt_pk_bf16_f32 v35, v65, v225
	v_cvt_pk_bf16_f32 v36, v38, v226
	v_cvt_pk_bf16_f32 v37, v39, v227
	v_exp_f32_e32 v46, v47
	s_waitcnt lgkmcnt(3)
	v_add_f32_e32 v253, v253, v46
	v_mfma_f32_32x32x16_bf16 v[18:33], v[114:117], v[34:37], v[18:33]
	v_exp_f32_e32 v45, v48
	v_exp_f32_e32 v47, v49
	v_add_f32_e32 v254, v254, v45
	s_waitcnt lgkmcnt(2)
	v_add_f32_e32 v255, v255, v47
	v_mfma_f32_32x32x16_bf16 v[2:17], v[110:113], v[34:37], v[2:17]
	v_cvt_pk_bf16_f32 v34, v40, v42
	v_cvt_pk_bf16_f32 v35, v41, v43
	v_cvt_pk_bf16_f32 v36, v44, v46
	v_cvt_pk_bf16_f32 v37, v45, v47
	s_waitcnt lgkmcnt(1)
	s_nop 0
	v_mfma_f32_32x32x16_bf16 v[18:33], v[106:109], v[34:37], v[18:33]
	s_nop 0
	s_waitcnt lgkmcnt(0)
	v_mfma_f32_32x32x16_bf16 v[2:17], v[102:105], v[34:37], v[2:17]
	s_setprio 0
